# first grid barrier: the 16 per-XCC census counters are loaded together (one wait) instead of one round trip each
# baseline (speedup 1.0000x reference)
.LBB0_557:
	v_readlane_b32 s2, v216, 20
	v_readlane_b32 s3, v216, 21
	s_mov_b64 s[4:5], -1
	s_nop 3
	global_load_dword v0, v1, s[2:3] sc1
	v_readlane_b32 s2, v216, 22
	v_readlane_b32 s3, v216, 23
	s_waitcnt lgkmcnt(0)
	s_nop 3
	global_load_dword v2, v1, s[2:3] sc1
	v_readlane_b32 s2, v216, 24
	v_readlane_b32 s3, v216, 25
	s_nop 0
	s_nop 0
	s_nop 2
	global_load_dword v3, v1, s[2:3] sc1
	v_readlane_b32 s2, v216, 26
	v_readlane_b32 s3, v216, 27
	s_nop 0
	s_nop 0
	s_nop 2
	global_load_dword v4, v1, s[2:3] sc1
	v_readlane_b32 s2, v216, 28
	v_readlane_b32 s3, v216, 29
	s_nop 0
	s_nop 0
	s_nop 2
	global_load_dword v5, v1, s[2:3] sc1
	v_readlane_b32 s2, v216, 30
	v_readlane_b32 s3, v216, 31
	s_nop 0
	s_nop 0
	s_nop 2
	global_load_dword v6, v1, s[2:3] sc1
	v_readlane_b32 s2, v216, 32
	v_readlane_b32 s3, v216, 33
	s_nop 0
	s_nop 0
	s_nop 2
	global_load_dword v7, v1, s[2:3] sc1
	v_readlane_b32 s2, v216, 34
	v_readlane_b32 s3, v216, 35
	s_nop 0
	s_nop 0
	s_nop 2
	global_load_dword v8, v1, s[2:3] sc1
	v_readlane_b32 s2, v216, 36
	v_readlane_b32 s3, v216, 37
	s_nop 0
	s_nop 0
	s_nop 2
	global_load_dword v9, v1, s[2:3] sc1
	v_readlane_b32 s2, v216, 38
	v_readlane_b32 s3, v216, 39
	s_nop 0
	s_nop 0
	s_nop 2
	global_load_dword v10, v1, s[2:3] sc1
	v_readlane_b32 s2, v216, 40
	v_readlane_b32 s3, v216, 41
	s_nop 0
	s_nop 0
	s_nop 2
	global_load_dword v11, v1, s[2:3] sc1
	v_readlane_b32 s2, v216, 42
	v_readlane_b32 s3, v216, 43
	s_nop 0
	s_nop 0
	s_nop 2
	global_load_dword v12, v1, s[2:3] sc1
	v_readlane_b32 s2, v216, 44
	v_readlane_b32 s3, v216, 45
	s_nop 0
	s_nop 0
	s_nop 2
	global_load_dword v13, v1, s[2:3] sc1
	v_readlane_b32 s2, v216, 46
	v_readlane_b32 s3, v216, 47
	s_nop 0
	s_nop 0
	s_nop 2
	global_load_dword v14, v1, s[2:3] sc1
	v_readlane_b32 s2, v216, 48
	v_readlane_b32 s3, v216, 49
	s_nop 0
	s_nop 0
	s_nop 2
	global_load_dword v15, v1, s[2:3] sc1
	v_readlane_b32 s2, v216, 50
	v_readlane_b32 s3, v216, 51
	s_nop 0
	s_nop 0
	s_nop 2
	global_load_dword v16, v1, s[2:3] sc1
	s_mov_b64 s[2:3], -1
	s_nop 0
	s_nop 0
	s_waitcnt vmcnt(0)
	v_add_u32_e32 v17, v2, v0
	v_add_u32_e32 v17, v17, v3
	v_add_u32_e32 v17, v17, v4
	v_add_u32_e32 v17, v17, v5
	v_add_u32_e32 v17, v17, v6
	v_add_u32_e32 v17, v17, v7
	v_add_u32_e32 v17, v17, v8
	v_add_u32_e32 v17, v17, v9
	v_add_u32_e32 v17, v17, v10
	v_add_u32_e32 v17, v17, v11
	v_add_u32_e32 v17, v17, v12
	v_add_u32_e32 v17, v17, v13
	v_add_u32_e32 v17, v17, v14
	v_add_u32_e32 v17, v17, v15
	v_add_u32_e32 v17, v17, v16
	v_cmp_eq_u32_e32 vcc, s86, v17
	s_cbranch_vccnz .LBB0_556
	s_and_b32 s2, s8, 0xff
	s_cmp_eq_u32 s2, 0
	s_mov_b64 s[2:3], -1
	s_mov_b64 s[6:7], -1
	s_sleep 1
	s_cbranch_scc0 .LBB0_561
	v_readlane_b32 s2, v216, 18
	v_readlane_b32 s3, v216, 19
	s_nop 4
	global_load_dword v17, v1, s[2:3] sc1
	s_waitcnt vmcnt(0)
	v_cmp_eq_u32_e32 vcc, 0, v17
	s_cbranch_vccnz .LBB0_563
	s_mov_b64 s[6:7], 0
	s_mov_b64 s[2:3], -1
